# combo8 + 56 bytes of padding after the attention code so the later K-loops keep combo3's code alignment
# speedup vs baseline: 1.0087x; 1.0052x over previous
.LBB0_599:
	s_nop 0
	s_nop 0
	s_nop 0
	s_nop 0
	s_nop 0
	s_nop 0
	s_nop 0
	s_nop 0
	s_nop 0
	s_nop 0
	s_nop 0
	s_nop 0
	s_nop 0
	s_nop 0
	s_mov_b32 s8, -1
	s_add_u32 s10, s18, 0x35600000
	v_mbcnt_lo_u32_b32 v0, s8, 0
	v_mbcnt_hi_u32_b32 v0, s8, v0
	v_add_u32_e32 v0, s76, v0
	v_readlane_b32 s8, v254, 25
	v_and_b32_e32 v72, 0xff, v0
	s_addc_u32 s11, s19, 0
	v_add_u32_e32 v35, s8, v0
	v_readfirstlane_b32 s14, v72
	s_mov_b32 s8, 0x80000
	s_mov_b64 s[12:13], -1
	s_cmp_gt_u32 s14, 63
	v_cmp_gt_i32_e64 s[8:9], s8, v35
	s_cbranch_scc0 .LBB0_618
	s_lshr_b32 s14, s14, 6
	s_cmp_lt_i32 s14, 2
	s_cbranch_scc1 .LBB0_612
	s_cmp_lg_u32 s14, 2
	s_cbranch_scc0 .LBB0_606
	s_and_saveexec_b64 s[12:13], s[8:9]
	s_movk_i32 s20, 0x800
	s_movk_i32 s21, 0x7ff
	s_movk_i32 s22, 0x6000
	s_mov_b32 s23, 0xd000
	s_mov_b32 s27, 0x13000
	s_movk_i32 s28, 0x7fe
	s_movk_i32 s34, 0x7fd
	s_mov_b32 s35, 0x77fff
	s_mov_b64 s[42:43], 0x1800
	s_cbranch_execz .LBB0_605
	v_lshlrev_b32_e32 v2, 3, v72
	v_lshlrev_b32_e32 v0, 4, v72
	v_lshl_add_u64 v[68:69], s[10:11], 0, v[0:1]
	s_mov_b64 s[14:15], 0
	v_lshlrev_b32_e32 v0, 1, v2
	v_mov_b32_e32 v73, v35
